# P7b balance: sample-row RG-LRU tasks moved from the two-task workgroups to one-task workgroups, together with the recurrence producer/consumer loop edits (S=7)
# baseline (speedup 1.0000x reference)
; #define INP(k) karg_in(k)
; #define tid opq((wave << 6) | lane_now())
; __device__ __forceinline__ void rglru_task(const Params& P, LAS unsigned char* lds, int b, int n, int qd, int tid, int t0, int t1) {
;     ...
;     const int cb0 = n * 128, oc0 = cb0 + qd * 32;
;     const bool prompt = b >= 0;
;     for (int i = tid; i < 640; i += NTHR) cw[i] = i < 512 ? INP(15)[(size_t)(i >> 7) * D + cb0 + (i & 127)] : INP(16)[cb0 + (i - 512)];
; __global__ void __launch_bounds__(NTHR, 2) fwd_megakernel(Params P) {
;     ...
;             if (wg < 96) rglru_task(P, lds, -1, (wg - 64) >> 2, (wg - 64) & 3, tid, 0, 1);
.LBB0_1763:
	s_sub_i32 s3, s2, 0x80
	s_cmpk_gt_u32 s3, 0x1f
	s_cbranch_scc1 .LBB0_1784
	v_mov_b32_e32 v47, v167
	s_load_dwordx2 s[14:15], s[0:1], 0x108
	s_load_dwordx2 s[6:7], s[0:1], 0x108
	s_load_dwordx2 s[8:9], s[0:1], 0x108
	s_sub_i32 s3, s2, 0x80
	s_lshr_b32 s18, s3, 2
	s_movk_i32 s3, 0x280
	s_lshl_b32 s4, s18, 7
	v_cmp_gt_i32_e32 vcc, s3, v47
	v_lshl_add_u32 v4, v47, 2, 0
	s_and_saveexec_b64 s[10:11], vcc
	s_cbranch_execz .LBB0_1771
	v_and_b32_e32 v0, 0x7f, v47
	s_mov_b32 s5, 0
	s_movk_i32 s3, 0x7f
	v_mov_b32_e32 v1, 0
	v_add_u32_e32 v7, 0xfffffe00, v47
	v_add_u32_e32 v5, 0x15880, v4
	s_mov_b64 s[12:13], 0
	s_movk_i32 s19, 0x1ff
	v_lshlrev_b32_e32 v0, 2, v0
	s_branch .LBB0_1767
